# final RMSNorm rewritten (5 rows in flight) + attention ATT_STORE gate loads hoisted with counted waits
# speedup vs baseline: 1.0387x; 1.0153x over previous
.LBB0_10:
	v_readlane_b32 s20, v248, 0
	s_nop 1
	v_writelane_b32 v246, s20, 40
	v_readlane_b32 s0, v248, 19
	v_readlane_b32 s1, v248, 20
	s_movk_i32 s53, 0x140
	s_mov_b64 s[22:23], -1
	s_mov_b64 s[20:21], 0
	s_cmp_lt_i32 s0, 1
	s_mov_b64 s[0:1], 0
	s_cbranch_scc1 .LBB0_18
	v_readlane_b32 s0, v248, 19
	s_cmp_gt_i32 s0, 13
	v_readlane_b32 s1, v248, 20
	s_cbranch_scc0 .LBB0_21
	v_readlane_b32 s0, v248, 19
	v_readlane_b32 s1, v248, 20
	s_cmp_eq_u32 s0, 14
	s_mov_b64 s[0:1], -1
	s_cbranch_scc0 .LBB0_17
	s_waitcnt lgkmcnt(0)
	s_mov_b64 s[22:23], exec
	v_readlane_b32 s0, v248, 41
	v_lshrrev_b32_e32 v210, 6, v0
	v_readlane_b32 s1, v246, 41
	v_readlane_b32 s40, v248, 5
	v_readfirstlane_b32 s2, v210
	v_readlane_b32 s41, v248, 6
	v_readlane_b32 s42, v248, 7
	v_readlane_b32 s43, v248, 8
	v_and_b32_e32 v211, 63, v0
	v_lshlrev_b32_e32 v211, 4, v211
	s_add_i32 s34, s0, s2
	s_lshl_b32 s35, s1, 2
	global_load_dwordx4 v[82:85], v211, s[40:41]
	global_load_dwordx4 v[86:89], v211, s[40:41] offset:1024
	global_load_dwordx4 v[90:93], v211, s[40:41] offset:2048
	global_load_dwordx4 v[94:97], v211, s[40:41] offset:3072
.Lnormf_iter:
	s_cmp_ge_u32 s34, 0x2800
	s_cbranch_scc1 .Lnormf_done
	s_mov_b32 s50, s34
	s_cmp_lt_u32 s50, 0x2800
	s_cselect_b32 s51, s50, s34
	s_lshl_b32 s51, s51, 12
	s_add_u32 s36, s42, s51
	s_addc_u32 s37, s43, 0
	global_load_dwordx4 v[2:5], v211, s[36:37]
	global_load_dwordx4 v[6:9], v211, s[36:37] offset:1024
	global_load_dwordx4 v[10:13], v211, s[36:37] offset:2048
	global_load_dwordx4 v[14:17], v211, s[36:37] offset:3072
	s_add_i32 s50, s50, s35
	s_cmp_lt_u32 s50, 0x2800
	s_cselect_b32 s51, s50, s34
	s_lshl_b32 s51, s51, 12
	s_add_u32 s38, s42, s51
	s_addc_u32 s39, s43, 0
	global_load_dwordx4 v[18:21], v211, s[38:39]
	global_load_dwordx4 v[22:25], v211, s[38:39] offset:1024
	global_load_dwordx4 v[26:29], v211, s[38:39] offset:2048
	global_load_dwordx4 v[30:33], v211, s[38:39] offset:3072
	s_add_i32 s50, s50, s35
	s_cmp_lt_u32 s50, 0x2800
	s_cselect_b32 s51, s50, s34
	s_lshl_b32 s51, s51, 12
	s_add_u32 s44, s42, s51
	s_addc_u32 s45, s43, 0
	global_load_dwordx4 v[34:37], v211, s[44:45]
	global_load_dwordx4 v[38:41], v211, s[44:45] offset:1024
	global_load_dwordx4 v[42:45], v211, s[44:45] offset:2048
	global_load_dwordx4 v[46:49], v211, s[44:45] offset:3072
	s_add_i32 s50, s50, s35
	s_cmp_lt_u32 s50, 0x2800
	s_cselect_b32 s51, s50, s34
	s_lshl_b32 s51, s51, 12
	s_add_u32 s46, s42, s51
	s_addc_u32 s47, s43, 0
	global_load_dwordx4 v[50:53], v211, s[46:47]
	global_load_dwordx4 v[54:57], v211, s[46:47] offset:1024
	global_load_dwordx4 v[58:61], v211, s[46:47] offset:2048
	global_load_dwordx4 v[62:65], v211, s[46:47] offset:3072
	s_add_i32 s50, s50, s35
	s_cmp_lt_u32 s50, 0x2800
	s_cselect_b32 s51, s50, s34
	s_lshl_b32 s51, s51, 12
	s_add_u32 s48, s42, s51
	s_addc_u32 s49, s43, 0
	global_load_dwordx4 v[66:69], v211, s[48:49]
	global_load_dwordx4 v[70:73], v211, s[48:49] offset:1024
	global_load_dwordx4 v[74:77], v211, s[48:49] offset:2048
	global_load_dwordx4 v[78:81], v211, s[48:49] offset:3072
	s_waitcnt vmcnt(16)
	v_mul_f32_e32 v213, v2, v2
	v_fmac_f32_e32 v213, v3, v3
	v_fmac_f32_e32 v213, v4, v4
	v_fmac_f32_e32 v213, v5, v5
	v_fmac_f32_e32 v213, v6, v6
	v_fmac_f32_e32 v213, v7, v7
	v_fmac_f32_e32 v213, v8, v8
	v_fmac_f32_e32 v213, v9, v9
	v_fmac_f32_e32 v213, v10, v10
	v_fmac_f32_e32 v213, v11, v11
	v_fmac_f32_e32 v213, v12, v12
	v_fmac_f32_e32 v213, v13, v13
	v_fmac_f32_e32 v213, v14, v14
	v_fmac_f32_e32 v213, v15, v15
	v_fmac_f32_e32 v213, v16, v16
	v_fmac_f32_e32 v213, v17, v17
	s_nop 1
	v_add_f32_dpp v213, v213, v213 quad_perm:[1,0,3,2] row_mask:0xf bank_mask:0xf
	s_nop 1
	v_add_f32_dpp v213, v213, v213 quad_perm:[2,3,0,1] row_mask:0xf bank_mask:0xf
	s_nop 1
	v_add_f32_dpp v213, v213, v213 row_ror:4 row_mask:0xf bank_mask:0xf
	s_nop 1
	v_add_f32_dpp v213, v213, v213 row_ror:8 row_mask:0xf bank_mask:0xf
	s_nop 1
	v_add_f32_dpp v213, v213, v213 row_bcast:15 row_mask:0xa bank_mask:0xf
	s_nop 1
	v_add_f32_dpp v213, v213, v213 row_bcast:31 row_mask:0xc bank_mask:0xf
	s_nop 1
	v_readlane_b32 s51, v213, 63
	s_nop 1
	v_mov_b32_e32 v214, s51
	v_fmamk_f32 v214, v214, 0x3a800000, v148
	v_rsq_f32_e32 v214, v214
	s_nop 0
	v_pk_mul_f32 v[2:3], v[2:3], v[214:215] op_sel_hi:[1,0]
	v_pk_mul_f32 v[4:5], v[4:5], v[214:215] op_sel_hi:[1,0]
	v_pk_mul_f32 v[6:7], v[6:7], v[214:215] op_sel_hi:[1,0]
	v_pk_mul_f32 v[8:9], v[8:9], v[214:215] op_sel_hi:[1,0]
	v_pk_mul_f32 v[10:11], v[10:11], v[214:215] op_sel_hi:[1,0]
	v_pk_mul_f32 v[12:13], v[12:13], v[214:215] op_sel_hi:[1,0]
	v_pk_mul_f32 v[14:15], v[14:15], v[214:215] op_sel_hi:[1,0]
	v_pk_mul_f32 v[16:17], v[16:17], v[214:215] op_sel_hi:[1,0]
	v_pk_mul_f32 v[2:3], v[2:3], v[82:83]
	v_pk_mul_f32 v[4:5], v[4:5], v[84:85]
	v_pk_mul_f32 v[6:7], v[6:7], v[86:87]
	v_pk_mul_f32 v[8:9], v[8:9], v[88:89]
	v_pk_mul_f32 v[10:11], v[10:11], v[90:91]
	v_pk_mul_f32 v[12:13], v[12:13], v[92:93]
	v_pk_mul_f32 v[14:15], v[14:15], v[94:95]
	v_pk_mul_f32 v[16:17], v[16:17], v[96:97]
	global_store_dwordx4 v211, v[2:5], s[36:37]
	global_store_dwordx4 v211, v[6:9], s[36:37] offset:1024
	global_store_dwordx4 v211, v[10:13], s[36:37] offset:2048
	global_store_dwordx4 v211, v[14:17], s[36:37] offset:3072
	s_waitcnt vmcnt(16)
	v_mul_f32_e32 v213, v18, v18
	v_fmac_f32_e32 v213, v19, v19
	v_fmac_f32_e32 v213, v20, v20
	v_fmac_f32_e32 v213, v21, v21
	v_fmac_f32_e32 v213, v22, v22
	v_fmac_f32_e32 v213, v23, v23
	v_fmac_f32_e32 v213, v24, v24
	v_fmac_f32_e32 v213, v25, v25
	v_fmac_f32_e32 v213, v26, v26
	v_fmac_f32_e32 v213, v27, v27
	v_fmac_f32_e32 v213, v28, v28
	v_fmac_f32_e32 v213, v29, v29
	v_fmac_f32_e32 v213, v30, v30
	v_fmac_f32_e32 v213, v31, v31
	v_fmac_f32_e32 v213, v32, v32
	v_fmac_f32_e32 v213, v33, v33
	s_nop 1
	v_add_f32_dpp v213, v213, v213 quad_perm:[1,0,3,2] row_mask:0xf bank_mask:0xf
	s_nop 1
	v_add_f32_dpp v213, v213, v213 quad_perm:[2,3,0,1] row_mask:0xf bank_mask:0xf
	s_nop 1
	v_add_f32_dpp v213, v213, v213 row_ror:4 row_mask:0xf bank_mask:0xf
	s_nop 1
	v_add_f32_dpp v213, v213, v213 row_ror:8 row_mask:0xf bank_mask:0xf
	s_nop 1
	v_add_f32_dpp v213, v213, v213 row_bcast:15 row_mask:0xa bank_mask:0xf
	s_nop 1
	v_add_f32_dpp v213, v213, v213 row_bcast:31 row_mask:0xc bank_mask:0xf
	s_nop 1
	v_readlane_b32 s51, v213, 63
	s_nop 1
	v_mov_b32_e32 v214, s51
	v_fmamk_f32 v214, v214, 0x3a800000, v148
	v_rsq_f32_e32 v214, v214
	s_nop 0
	v_pk_mul_f32 v[18:19], v[18:19], v[214:215] op_sel_hi:[1,0]
	v_pk_mul_f32 v[20:21], v[20:21], v[214:215] op_sel_hi:[1,0]
	v_pk_mul_f32 v[22:23], v[22:23], v[214:215] op_sel_hi:[1,0]
	v_pk_mul_f32 v[24:25], v[24:25], v[214:215] op_sel_hi:[1,0]
	v_pk_mul_f32 v[26:27], v[26:27], v[214:215] op_sel_hi:[1,0]
	v_pk_mul_f32 v[28:29], v[28:29], v[214:215] op_sel_hi:[1,0]
	v_pk_mul_f32 v[30:31], v[30:31], v[214:215] op_sel_hi:[1,0]
	v_pk_mul_f32 v[32:33], v[32:33], v[214:215] op_sel_hi:[1,0]
	v_pk_mul_f32 v[18:19], v[18:19], v[82:83]
	v_pk_mul_f32 v[20:21], v[20:21], v[84:85]
	v_pk_mul_f32 v[22:23], v[22:23], v[86:87]
	v_pk_mul_f32 v[24:25], v[24:25], v[88:89]
	v_pk_mul_f32 v[26:27], v[26:27], v[90:91]
	v_pk_mul_f32 v[28:29], v[28:29], v[92:93]
	v_pk_mul_f32 v[30:31], v[30:31], v[94:95]
	v_pk_mul_f32 v[32:33], v[32:33], v[96:97]
	global_store_dwordx4 v211, v[18:21], s[38:39]
	global_store_dwordx4 v211, v[22:25], s[38:39] offset:1024
	global_store_dwordx4 v211, v[26:29], s[38:39] offset:2048
	global_store_dwordx4 v211, v[30:33], s[38:39] offset:3072
	s_waitcnt vmcnt(16)
	v_mul_f32_e32 v213, v34, v34
	v_fmac_f32_e32 v213, v35, v35
	v_fmac_f32_e32 v213, v36, v36
	v_fmac_f32_e32 v213, v37, v37
	v_fmac_f32_e32 v213, v38, v38
	v_fmac_f32_e32 v213, v39, v39
	v_fmac_f32_e32 v213, v40, v40
	v_fmac_f32_e32 v213, v41, v41
	v_fmac_f32_e32 v213, v42, v42
	v_fmac_f32_e32 v213, v43, v43
	v_fmac_f32_e32 v213, v44, v44
	v_fmac_f32_e32 v213, v45, v45
	v_fmac_f32_e32 v213, v46, v46
	v_fmac_f32_e32 v213, v47, v47
	v_fmac_f32_e32 v213, v48, v48
	v_fmac_f32_e32 v213, v49, v49
	s_nop 1
	v_add_f32_dpp v213, v213, v213 quad_perm:[1,0,3,2] row_mask:0xf bank_mask:0xf
	s_nop 1
	v_add_f32_dpp v213, v213, v213 quad_perm:[2,3,0,1] row_mask:0xf bank_mask:0xf
	s_nop 1
	v_add_f32_dpp v213, v213, v213 row_ror:4 row_mask:0xf bank_mask:0xf
	s_nop 1
	v_add_f32_dpp v213, v213, v213 row_ror:8 row_mask:0xf bank_mask:0xf
	s_nop 1
	v_add_f32_dpp v213, v213, v213 row_bcast:15 row_mask:0xa bank_mask:0xf
	s_nop 1
	v_add_f32_dpp v213, v213, v213 row_bcast:31 row_mask:0xc bank_mask:0xf
	s_nop 1
	v_readlane_b32 s51, v213, 63
	s_nop 1
	v_mov_b32_e32 v214, s51
	v_fmamk_f32 v214, v214, 0x3a800000, v148
	v_rsq_f32_e32 v214, v214
	s_nop 0
	v_pk_mul_f32 v[34:35], v[34:35], v[214:215] op_sel_hi:[1,0]
	v_pk_mul_f32 v[36:37], v[36:37], v[214:215] op_sel_hi:[1,0]
	v_pk_mul_f32 v[38:39], v[38:39], v[214:215] op_sel_hi:[1,0]
	v_pk_mul_f32 v[40:41], v[40:41], v[214:215] op_sel_hi:[1,0]
	v_pk_mul_f32 v[42:43], v[42:43], v[214:215] op_sel_hi:[1,0]
	v_pk_mul_f32 v[44:45], v[44:45], v[214:215] op_sel_hi:[1,0]
	v_pk_mul_f32 v[46:47], v[46:47], v[214:215] op_sel_hi:[1,0]
	v_pk_mul_f32 v[48:49], v[48:49], v[214:215] op_sel_hi:[1,0]
	v_pk_mul_f32 v[34:35], v[34:35], v[82:83]
	v_pk_mul_f32 v[36:37], v[36:37], v[84:85]
	v_pk_mul_f32 v[38:39], v[38:39], v[86:87]
	v_pk_mul_f32 v[40:41], v[40:41], v[88:89]
	v_pk_mul_f32 v[42:43], v[42:43], v[90:91]
	v_pk_mul_f32 v[44:45], v[44:45], v[92:93]
	v_pk_mul_f32 v[46:47], v[46:47], v[94:95]
	v_pk_mul_f32 v[48:49], v[48:49], v[96:97]
	global_store_dwordx4 v211, v[34:37], s[44:45]
	global_store_dwordx4 v211, v[38:41], s[44:45] offset:1024
	global_store_dwordx4 v211, v[42:45], s[44:45] offset:2048
	global_store_dwordx4 v211, v[46:49], s[44:45] offset:3072
	s_waitcnt vmcnt(16)
	v_mul_f32_e32 v213, v50, v50
	v_fmac_f32_e32 v213, v51, v51
	v_fmac_f32_e32 v213, v52, v52
	v_fmac_f32_e32 v213, v53, v53
	v_fmac_f32_e32 v213, v54, v54
	v_fmac_f32_e32 v213, v55, v55
	v_fmac_f32_e32 v213, v56, v56
	v_fmac_f32_e32 v213, v57, v57
	v_fmac_f32_e32 v213, v58, v58
	v_fmac_f32_e32 v213, v59, v59
	v_fmac_f32_e32 v213, v60, v60
	v_fmac_f32_e32 v213, v61, v61
	v_fmac_f32_e32 v213, v62, v62
	v_fmac_f32_e32 v213, v63, v63
	v_fmac_f32_e32 v213, v64, v64
	v_fmac_f32_e32 v213, v65, v65
	s_nop 1
	v_add_f32_dpp v213, v213, v213 quad_perm:[1,0,3,2] row_mask:0xf bank_mask:0xf
	s_nop 1
	v_add_f32_dpp v213, v213, v213 quad_perm:[2,3,0,1] row_mask:0xf bank_mask:0xf
	s_nop 1
	v_add_f32_dpp v213, v213, v213 row_ror:4 row_mask:0xf bank_mask:0xf
	s_nop 1
	v_add_f32_dpp v213, v213, v213 row_ror:8 row_mask:0xf bank_mask:0xf
	s_nop 1
	v_add_f32_dpp v213, v213, v213 row_bcast:15 row_mask:0xa bank_mask:0xf
	s_nop 1
	v_add_f32_dpp v213, v213, v213 row_bcast:31 row_mask:0xc bank_mask:0xf
	s_nop 1
	v_readlane_b32 s51, v213, 63
	s_nop 1
	v_mov_b32_e32 v214, s51
	v_fmamk_f32 v214, v214, 0x3a800000, v148
	v_rsq_f32_e32 v214, v214
	s_nop 0
	v_pk_mul_f32 v[50:51], v[50:51], v[214:215] op_sel_hi:[1,0]
	v_pk_mul_f32 v[52:53], v[52:53], v[214:215] op_sel_hi:[1,0]
	v_pk_mul_f32 v[54:55], v[54:55], v[214:215] op_sel_hi:[1,0]
	v_pk_mul_f32 v[56:57], v[56:57], v[214:215] op_sel_hi:[1,0]
	v_pk_mul_f32 v[58:59], v[58:59], v[214:215] op_sel_hi:[1,0]
	v_pk_mul_f32 v[60:61], v[60:61], v[214:215] op_sel_hi:[1,0]
	v_pk_mul_f32 v[62:63], v[62:63], v[214:215] op_sel_hi:[1,0]
	v_pk_mul_f32 v[64:65], v[64:65], v[214:215] op_sel_hi:[1,0]
	v_pk_mul_f32 v[50:51], v[50:51], v[82:83]
	v_pk_mul_f32 v[52:53], v[52:53], v[84:85]
	v_pk_mul_f32 v[54:55], v[54:55], v[86:87]
	v_pk_mul_f32 v[56:57], v[56:57], v[88:89]
	v_pk_mul_f32 v[58:59], v[58:59], v[90:91]
	v_pk_mul_f32 v[60:61], v[60:61], v[92:93]
	v_pk_mul_f32 v[62:63], v[62:63], v[94:95]
	v_pk_mul_f32 v[64:65], v[64:65], v[96:97]
	global_store_dwordx4 v211, v[50:53], s[46:47]
	global_store_dwordx4 v211, v[54:57], s[46:47] offset:1024
	global_store_dwordx4 v211, v[58:61], s[46:47] offset:2048
	global_store_dwordx4 v211, v[62:65], s[46:47] offset:3072
	s_waitcnt vmcnt(16)
	v_mul_f32_e32 v213, v66, v66
	v_fmac_f32_e32 v213, v67, v67
	v_fmac_f32_e32 v213, v68, v68
	v_fmac_f32_e32 v213, v69, v69
	v_fmac_f32_e32 v213, v70, v70
	v_fmac_f32_e32 v213, v71, v71
	v_fmac_f32_e32 v213, v72, v72
	v_fmac_f32_e32 v213, v73, v73
	v_fmac_f32_e32 v213, v74, v74
	v_fmac_f32_e32 v213, v75, v75
	v_fmac_f32_e32 v213, v76, v76
	v_fmac_f32_e32 v213, v77, v77
	v_fmac_f32_e32 v213, v78, v78
	v_fmac_f32_e32 v213, v79, v79
	v_fmac_f32_e32 v213, v80, v80
	v_fmac_f32_e32 v213, v81, v81
	s_nop 1
	v_add_f32_dpp v213, v213, v213 quad_perm:[1,0,3,2] row_mask:0xf bank_mask:0xf
	s_nop 1
	v_add_f32_dpp v213, v213, v213 quad_perm:[2,3,0,1] row_mask:0xf bank_mask:0xf
	s_nop 1
	v_add_f32_dpp v213, v213, v213 row_ror:4 row_mask:0xf bank_mask:0xf
	s_nop 1
	v_add_f32_dpp v213, v213, v213 row_ror:8 row_mask:0xf bank_mask:0xf
	s_nop 1
	v_add_f32_dpp v213, v213, v213 row_bcast:15 row_mask:0xa bank_mask:0xf
	s_nop 1
	v_add_f32_dpp v213, v213, v213 row_bcast:31 row_mask:0xc bank_mask:0xf
	s_nop 1
	v_readlane_b32 s51, v213, 63
	s_nop 1
	v_mov_b32_e32 v214, s51
	v_fmamk_f32 v214, v214, 0x3a800000, v148
	v_rsq_f32_e32 v214, v214
	s_nop 0
	v_pk_mul_f32 v[66:67], v[66:67], v[214:215] op_sel_hi:[1,0]
	v_pk_mul_f32 v[68:69], v[68:69], v[214:215] op_sel_hi:[1,0]
	v_pk_mul_f32 v[70:71], v[70:71], v[214:215] op_sel_hi:[1,0]
	v_pk_mul_f32 v[72:73], v[72:73], v[214:215] op_sel_hi:[1,0]
	v_pk_mul_f32 v[74:75], v[74:75], v[214:215] op_sel_hi:[1,0]
	v_pk_mul_f32 v[76:77], v[76:77], v[214:215] op_sel_hi:[1,0]
	v_pk_mul_f32 v[78:79], v[78:79], v[214:215] op_sel_hi:[1,0]
	v_pk_mul_f32 v[80:81], v[80:81], v[214:215] op_sel_hi:[1,0]
	v_pk_mul_f32 v[66:67], v[66:67], v[82:83]
	v_pk_mul_f32 v[68:69], v[68:69], v[84:85]
	v_pk_mul_f32 v[70:71], v[70:71], v[86:87]
	v_pk_mul_f32 v[72:73], v[72:73], v[88:89]
	v_pk_mul_f32 v[74:75], v[74:75], v[90:91]
	v_pk_mul_f32 v[76:77], v[76:77], v[92:93]
	v_pk_mul_f32 v[78:79], v[78:79], v[94:95]
	v_pk_mul_f32 v[80:81], v[80:81], v[96:97]
	global_store_dwordx4 v211, v[66:69], s[48:49]
	global_store_dwordx4 v211, v[70:73], s[48:49] offset:1024
	global_store_dwordx4 v211, v[74:77], s[48:49] offset:2048
	global_store_dwordx4 v211, v[78:81], s[48:49] offset:3072
	s_mul_i32 s50, s35, 5
	s_add_i32 s34, s34, s50
	s_branch .Lnormf_iter
.Lnormf_done:
.LBB0_16:
	s_or_b64 exec, exec, s[22:23]
	s_mov_b64 s[0:1], 0
.LBB0_17:
	s_branch .LBB0_39

.LBB0_106:
	v_sub_f32_e32 v34, v34, v67
	v_exp_f32_e32 v69, v34
	v_sub_f32_e32 v34, v35, v67
	v_exp_f32_e32 v70, v34
	v_sub_f32_e32 v34, v36, v67
	v_exp_f32_e32 v71, v34
	v_sub_f32_e32 v34, v37, v67
	v_exp_f32_e32 v72, v34
	v_sub_f32_e32 v34, v38, v67
	v_exp_f32_e32 v73, v34
	v_sub_f32_e32 v34, v39, v67
	v_exp_f32_e32 v74, v34
	v_sub_f32_e32 v34, v40, v67
	v_exp_f32_e32 v75, v34
	v_sub_f32_e32 v34, v41, v67
	v_exp_f32_e32 v76, v34
	v_sub_f32_e32 v34, v42, v67
	v_exp_f32_e32 v77, v34
	v_sub_f32_e32 v34, v43, v67
	v_exp_f32_e32 v78, v34
	v_sub_f32_e32 v34, v44, v67
	v_sub_f32_e32 v50, v50, v67
	v_sub_f32_e32 v51, v51, v67
	v_exp_f32_e32 v79, v34
	v_sub_f32_e32 v34, v45, v67
	v_exp_f32_e32 v50, v50
	v_exp_f32_e32 v51, v51
	v_exp_f32_e32 v80, v34
	v_sub_f32_e32 v34, v46, v67
	v_exp_f32_e32 v46, v34
	v_sub_f32_e32 v34, v47, v67
	v_exp_f32_e32 v47, v34
	v_sub_f32_e32 v34, v48, v67
	v_sub_f32_e32 v52, v52, v67
	v_sub_f32_e32 v53, v53, v67
	v_sub_f32_e32 v54, v54, v67
	v_sub_f32_e32 v55, v55, v67
	v_sub_f32_e32 v56, v56, v67
	v_sub_f32_e32 v57, v57, v67
	v_exp_f32_e32 v48, v34
	v_sub_f32_e32 v34, v49, v67
	v_add_f32_e32 v68, 0, v50
	v_exp_f32_e32 v52, v52
	v_exp_f32_e32 v53, v53
	v_exp_f32_e32 v54, v54
	v_exp_f32_e32 v55, v55
	v_exp_f32_e32 v56, v56
	v_exp_f32_e32 v57, v57
	v_exp_f32_e32 v49, v34
	v_cvt_pk_bf16_f32 v34, v50, v51
	v_add_u32_e32 v50, 0x4800, v180
	ds_read2_b64 v[38:41], v50 offset1:2
	ds_read2_b64 v[42:45], v50 offset0:4 offset1:6
	v_add_f32_e32 v68, v51, v68
	v_cvt_pk_bf16_f32 v35, v52, v53
	v_cvt_pk_bf16_f32 v36, v54, v55
	v_cvt_pk_bf16_f32 v37, v56, v57
	v_add_u32_e32 v51, 0x5800, v180
	v_sub_f32_e32 v58, v58, v67
	s_waitcnt lgkmcnt(1)
	v_mfma_f32_32x32x16_bf16 v[18:33], v[38:41], v[34:37], v[18:33]
	ds_read2_b64 v[38:41], v51 offset0:32 offset1:34
	v_sub_f32_e32 v59, v59, v67
	v_sub_f32_e32 v60, v60, v67
	v_sub_f32_e32 v61, v61, v67
	v_sub_f32_e32 v62, v62, v67
	v_sub_f32_e32 v63, v63, v67
	v_sub_f32_e32 v64, v64, v67
	s_waitcnt lgkmcnt(0)
	v_mfma_f32_32x32x16_bf16 v[2:17], v[38:41], v[34:37], v[2:17]
	ds_read2_b64 v[38:41], v51 offset0:36 offset1:38
	v_sub_f32_e32 v65, v65, v67
	v_exp_f32_e32 v58, v58
	v_exp_f32_e32 v59, v59
	v_exp_f32_e32 v60, v60
	v_exp_f32_e32 v61, v61
	v_exp_f32_e32 v62, v62
	v_exp_f32_e32 v63, v63
	v_exp_f32_e32 v64, v64
	v_exp_f32_e32 v65, v65
	v_cvt_pk_bf16_f32 v34, v58, v59
	v_cvt_pk_bf16_f32 v35, v60, v61
	v_cvt_pk_bf16_f32 v36, v62, v63
	v_cvt_pk_bf16_f32 v37, v64, v65
	v_add_f32_e32 v68, v52, v68
	v_add_f32_e32 v68, v53, v68
	s_waitcnt lgkmcnt(0)
	v_mfma_f32_32x32x16_bf16 v[2:17], v[38:41], v[34:37], v[2:17]
	ds_read2_b64 v[38:41], v50 offset0:8 offset1:10
	v_add_f32_e32 v68, v54, v68
	v_add_f32_e32 v68, v55, v68
	v_add_f32_e32 v68, v56, v68
	v_add_f32_e32 v68, v57, v68
	v_add_f32_e32 v68, v58, v68
	v_add_f32_e32 v68, v59, v68
	v_mfma_f32_32x32x16_bf16 v[18:33], v[42:45], v[34:37], v[18:33]
	v_cvt_pk_bf16_f32 v34, v69, v70
	v_cvt_pk_bf16_f32 v35, v71, v72
	v_cvt_pk_bf16_f32 v36, v73, v74
	v_cvt_pk_bf16_f32 v37, v75, v76
	v_add_f32_e32 v68, v60, v68
	v_add_f32_e32 v68, v61, v68
	v_add_f32_e32 v68, v62, v68
	s_waitcnt lgkmcnt(0)
	v_mfma_f32_32x32x16_bf16 v[18:33], v[38:41], v[34:37], v[18:33]
	ds_read2_b64 v[38:41], v51 offset0:40 offset1:42
	v_add_f32_e32 v68, v63, v68
	v_add_f32_e32 v68, v64, v68
	v_add_f32_e32 v68, v65, v68
	s_and_b64 s[0:1], s[0:1], exec
	s_movk_i32 s0, 0x800
	s_cselect_b32 s0, s0, 0x300
	s_waitcnt lgkmcnt(0)
	v_mfma_f32_32x32x16_bf16 v[2:17], v[38:41], v[34:37], v[2:17]
	ds_read2_b64 v[38:41], v50 offset0:12 offset1:14
	v_cvt_pk_bf16_f32 v34, v77, v78
	v_cvt_pk_bf16_f32 v35, v79, v80
	v_cvt_pk_bf16_f32 v36, v46, v47
	v_cvt_pk_bf16_f32 v37, v48, v49
	s_add_i32 s0, s51, s0
	s_lshl_b32 s96, s0, 1
	s_waitcnt lgkmcnt(0)
	v_mfma_f32_32x32x16_bf16 v[18:33], v[38:41], v[34:37], v[18:33]
	ds_read2_b64 v[38:41], v51 offset0:44 offset1:46
	s_waitcnt lgkmcnt(0)
	s_barrier
	v_mfma_f32_32x32x16_bf16 v[2:17], v[38:41], v[34:37], v[2:17]
	v_add_f32_e32 v34, v69, v68
	v_add_f32_e32 v34, v70, v34
	v_add_f32_e32 v34, v71, v34
	v_add_f32_e32 v34, v72, v34
	v_add_f32_e32 v34, v73, v34
	v_add_f32_e32 v34, v74, v34
	v_add_f32_e32 v34, v75, v34
	v_add_f32_e32 v34, v76, v34
	v_add_f32_e32 v34, v77, v34
	v_add_f32_e32 v34, v78, v34
	v_add_f32_e32 v34, v79, v34
	v_add_f32_e32 v34, v80, v34
	v_add_f32_e32 v34, v46, v34
	v_add_f32_e32 v34, v47, v34
	v_add_f32_e32 v34, v48, v34
	v_add_f32_e32 v34, v49, v34
	v_add_f32_e32 v34, v34, v200
	ds_bpermute_b32 v35, v66, v34
	v_lshlrev_b32_e32 v40, 1, v108
	v_mov_b32_e32 v41, v147
	s_waitcnt lgkmcnt(0)
	v_add_f32_e32 v34, v34, v35
	v_div_scale_f32 v35, s[20:21], v34, v34, 1.0
	v_rcp_f32_e32 v36, v35
	s_nop 0
	v_fma_f32 v37, -v35, v36, 1.0
	v_fmac_f32_e32 v36, v37, v36
	v_div_scale_f32 v37, vcc, 1.0, v34, 1.0
	v_mul_f32_e32 v38, v37, v36
	v_fma_f32 v39, -v35, v38, v37
	v_fmac_f32_e32 v38, v39, v36
	v_fma_f32 v35, -v35, v38, v37
	v_div_fmas_f32 v35, v35, v36, v38
	v_lshl_add_u64 v[36:37], v[144:145], 0, s[96:97]
	v_lshl_add_u64 v[36:37], v[36:37], 0, v[40:41]
	global_load_dwordx2 v[42:43], v[36:37], off
	global_load_dwordx2 v[218:219], v[36:37], off offset:16
	global_load_dwordx2 v[220:221], v[36:37], off offset:32
	global_load_dwordx2 v[222:223], v[36:37], off offset:48
	global_load_dwordx2 v[224:225], v[36:37], off offset:64
	global_load_dwordx2 v[226:227], v[36:37], off offset:80
	global_load_dwordx2 v[228:229], v[36:37], off offset:96
	global_load_dwordx2 v[230:231], v[36:37], off offset:112
	v_div_fixup_f32 v34, v35, v34, 1.0
	v_mov_b64_e32 v[38:39], s[12:13]
	v_mad_i64_i32 v[38:39], s[0:1], v151, s30, v[38:39]
	v_pk_mul_f32 v[18:19], v[18:19], v[34:35] op_sel_hi:[1,0]
	s_lshl_b32 s0, s51, 1
	s_lshl_b32 s1, s59, 10
	s_or_b32 s96, s1, s0
	v_lshl_add_u64 v[38:39], v[38:39], 0, s[96:97]
	v_pk_mul_f32 v[22:23], v[22:23], v[34:35] op_sel_hi:[1,0]
	v_pk_mul_f32 v[24:25], v[24:25], v[34:35] op_sel_hi:[1,0]
	v_pk_mul_f32 v[2:3], v[2:3], v[34:35] op_sel_hi:[1,0]
	v_pk_mul_f32 v[4:5], v[4:5], v[34:35] op_sel_hi:[1,0]
	v_pk_mul_f32 v[6:7], v[6:7], v[34:35] op_sel_hi:[1,0]
	s_mov_b64 s[0:1], 0
	s_mov_b32 s96, 0x800000
	s_waitcnt vmcnt(7)
	v_lshlrev_b32_e32 v44, 16, v42
	v_and_b32_e32 v45, 0xffff0000, v42
	v_pk_mul_f32 v[18:19], v[18:19], v[44:45]
	v_lshlrev_b32_e32 v42, 16, v43
	v_and_b32_e32 v43, 0xffff0000, v43
	v_cvt_pk_bf16_f32 v44, v18, v19
	v_pk_mul_f32 v[18:19], v[20:21], v[34:35] op_sel_hi:[1,0]
	s_nop 0
	v_pk_mul_f32 v[18:19], v[18:19], v[42:43]
	s_nop 0
	v_cvt_pk_bf16_f32 v45, v18, v19
	v_lshl_add_u64 v[18:19], v[38:39], 0, v[40:41]
	global_store_dwordx2 v[18:19], v[44:45], off
	s_waitcnt vmcnt(7)
	v_mov_b32_e32 v20, v218
	v_mov_b32_e32 v21, v219
	v_lshlrev_b32_e32 v38, 16, v20
	v_and_b32_e32 v39, 0xffff0000, v20
	v_lshlrev_b32_e32 v20, 16, v21
	v_and_b32_e32 v21, 0xffff0000, v21
	v_pk_mul_f32 v[22:23], v[22:23], v[38:39]
	v_pk_mul_f32 v[20:21], v[24:25], v[20:21]
	v_cvt_pk_bf16_f32 v22, v22, v23
	v_cvt_pk_bf16_f32 v23, v20, v21
	global_store_dwordx2 v[18:19], v[22:23], off offset:16
	v_pk_mul_f32 v[24:25], v[26:27], v[34:35] op_sel_hi:[1,0]
	s_waitcnt vmcnt(7)
	v_mov_b32_e32 v20, v220
	v_mov_b32_e32 v21, v221
	v_lshlrev_b32_e32 v22, 16, v20
	v_and_b32_e32 v23, 0xffff0000, v20
	v_lshlrev_b32_e32 v20, 16, v21
	v_and_b32_e32 v21, 0xffff0000, v21
	v_pk_mul_f32 v[22:23], v[24:25], v[22:23]
	v_pk_mul_f32 v[24:25], v[28:29], v[34:35] op_sel_hi:[1,0]
	v_cvt_pk_bf16_f32 v22, v22, v23
	v_pk_mul_f32 v[20:21], v[24:25], v[20:21]
	v_pk_mul_f32 v[24:25], v[30:31], v[34:35] op_sel_hi:[1,0]
	v_cvt_pk_bf16_f32 v23, v20, v21
	global_store_dwordx2 v[18:19], v[22:23], off offset:32
	s_waitcnt vmcnt(7)
	v_mov_b32_e32 v20, v222
	v_mov_b32_e32 v21, v223
	v_lshlrev_b32_e32 v22, 16, v20
	v_and_b32_e32 v23, 0xffff0000, v20
	v_lshlrev_b32_e32 v20, 16, v21
	v_and_b32_e32 v21, 0xffff0000, v21
	v_pk_mul_f32 v[22:23], v[24:25], v[22:23]
	v_pk_mul_f32 v[24:25], v[32:33], v[34:35] op_sel_hi:[1,0]
	v_cvt_pk_bf16_f32 v22, v22, v23
	v_pk_mul_f32 v[20:21], v[24:25], v[20:21]
	s_nop 0
	v_cvt_pk_bf16_f32 v23, v20, v21
	global_store_dwordx2 v[18:19], v[22:23], off offset:48
	s_waitcnt vmcnt(7)
	v_mov_b32_e32 v20, v224
	v_mov_b32_e32 v21, v225
	v_lshlrev_b32_e32 v22, 16, v20
	v_and_b32_e32 v23, 0xffff0000, v20
	v_lshlrev_b32_e32 v20, 16, v21
	v_and_b32_e32 v21, 0xffff0000, v21
	v_pk_mul_f32 v[2:3], v[2:3], v[22:23]
	v_pk_mul_f32 v[4:5], v[4:5], v[20:21]
	v_cvt_pk_bf16_f32 v2, v2, v3
	v_cvt_pk_bf16_f32 v3, v4, v5
	global_store_dwordx2 v[18:19], v[2:3], off offset:64
	s_waitcnt vmcnt(7)
	v_mov_b32_e32 v2, v226
	v_mov_b32_e32 v3, v227
	v_lshlrev_b32_e32 v4, 16, v2
	v_and_b32_e32 v5, 0xffff0000, v2
	v_lshlrev_b32_e32 v2, 16, v3
	v_and_b32_e32 v3, 0xffff0000, v3
	v_pk_mul_f32 v[4:5], v[6:7], v[4:5]
	v_pk_mul_f32 v[6:7], v[8:9], v[34:35] op_sel_hi:[1,0]
	v_cvt_pk_bf16_f32 v4, v4, v5
	v_pk_mul_f32 v[2:3], v[6:7], v[2:3]
	v_pk_mul_f32 v[6:7], v[10:11], v[34:35] op_sel_hi:[1,0]
	v_cvt_pk_bf16_f32 v5, v2, v3
	global_store_dwordx2 v[18:19], v[4:5], off offset:80
	s_waitcnt vmcnt(7)
	v_mov_b32_e32 v2, v228
	v_mov_b32_e32 v3, v229
	v_lshlrev_b32_e32 v4, 16, v2
	v_and_b32_e32 v5, 0xffff0000, v2
	v_lshlrev_b32_e32 v2, 16, v3
	v_and_b32_e32 v3, 0xffff0000, v3
	v_pk_mul_f32 v[4:5], v[6:7], v[4:5]
	v_pk_mul_f32 v[6:7], v[12:13], v[34:35] op_sel_hi:[1,0]
	v_cvt_pk_bf16_f32 v4, v4, v5
	v_pk_mul_f32 v[2:3], v[6:7], v[2:3]
	v_pk_mul_f32 v[6:7], v[14:15], v[34:35] op_sel_hi:[1,0]
	v_cvt_pk_bf16_f32 v5, v2, v3
	global_store_dwordx2 v[18:19], v[4:5], off offset:96
	s_waitcnt vmcnt(7)
	v_mov_b32_e32 v2, v230
	v_mov_b32_e32 v3, v231
	v_lshlrev_b32_e32 v4, 16, v2
	v_and_b32_e32 v5, 0xffff0000, v2
	v_lshlrev_b32_e32 v2, 16, v3
	v_and_b32_e32 v3, 0xffff0000, v3
	v_pk_mul_f32 v[4:5], v[6:7], v[4:5]
	v_pk_mul_f32 v[6:7], v[16:17], v[34:35] op_sel_hi:[1,0]
	v_cvt_pk_bf16_f32 v4, v4, v5
	v_pk_mul_f32 v[2:3], v[6:7], v[2:3]
	s_nop 0
	v_cvt_pk_bf16_f32 v5, v2, v3
	global_store_dwordx2 v[18:19], v[4:5], off offset:112

.LBB0_109:
	ds_bpermute_b32 v34, v84, v87
	v_lshlrev_b32_e32 v40, 1, v108
	v_mov_b32_e32 v41, v147
	s_add_i32 s25, s25, 1
	s_waitcnt lgkmcnt(0)
	v_add_f32_e32 v34, v87, v34
	v_div_scale_f32 v35, s[20:21], v34, v34, 1.0
	v_rcp_f32_e32 v36, v35
	s_add_i32 s20, s2, s24
	s_lshl_b32 s20, s20, 1
	s_mov_b32 s21, s97
	v_fma_f32 v37, -v35, v36, 1.0
	v_fmac_f32_e32 v36, v37, v36
	v_div_scale_f32 v37, vcc, 1.0, v34, 1.0
	v_mul_f32_e32 v38, v37, v36
	v_fma_f32 v39, -v35, v38, v37
	v_fmac_f32_e32 v38, v39, v36
	v_fma_f32 v35, -v35, v38, v37
	v_div_fmas_f32 v35, v35, v36, v38
	v_lshl_add_u64 v[36:37], v[82:83], 0, s[20:21]
	v_lshl_add_u64 v[36:37], v[36:37], 0, v[40:41]
	global_load_dwordx2 v[42:43], v[36:37], off
	global_load_dwordx2 v[218:219], v[36:37], off offset:16
	global_load_dwordx2 v[220:221], v[36:37], off offset:32
	global_load_dwordx2 v[222:223], v[36:37], off offset:48
	global_load_dwordx2 v[224:225], v[36:37], off offset:64
	global_load_dwordx2 v[226:227], v[36:37], off offset:80
	global_load_dwordx2 v[228:229], v[36:37], off offset:96
	global_load_dwordx2 v[230:231], v[36:37], off offset:112
	v_div_fixup_f32 v34, v35, v34, 1.0
	v_mov_b64_e32 v[38:39], s[12:13]
	v_pk_mul_f32 v[18:19], v[18:19], v[34:35] op_sel_hi:[1,0]
	v_mad_i64_i32 v[38:39], s[20:21], v86, s30, v[38:39]
	s_add_i32 s2, s2, s38
	s_lshl_b32 s20, s2, 1
	s_mov_b32 s21, s97
	v_lshl_add_u64 v[38:39], v[38:39], 0, s[20:21]
	v_pk_mul_f32 v[22:23], v[22:23], v[34:35] op_sel_hi:[1,0]
	v_pk_mul_f32 v[24:25], v[24:25], v[34:35] op_sel_hi:[1,0]
	v_pk_mul_f32 v[2:3], v[2:3], v[34:35] op_sel_hi:[1,0]
	v_pk_mul_f32 v[4:5], v[4:5], v[34:35] op_sel_hi:[1,0]
	v_pk_mul_f32 v[6:7], v[6:7], v[34:35] op_sel_hi:[1,0]
	s_cmp_eq_u32 s25, 4
	s_waitcnt vmcnt(7)
	v_lshlrev_b32_e32 v44, 16, v42
	v_and_b32_e32 v45, 0xffff0000, v42
	v_pk_mul_f32 v[18:19], v[18:19], v[44:45]
	v_lshlrev_b32_e32 v42, 16, v43
	v_and_b32_e32 v43, 0xffff0000, v43
	v_cvt_pk_bf16_f32 v44, v18, v19
	v_pk_mul_f32 v[18:19], v[20:21], v[34:35] op_sel_hi:[1,0]
	s_nop 0
	v_pk_mul_f32 v[18:19], v[18:19], v[42:43]
	s_nop 0
	v_cvt_pk_bf16_f32 v45, v18, v19
	v_lshl_add_u64 v[18:19], v[38:39], 0, v[40:41]
	global_store_dwordx2 v[18:19], v[44:45], off
	s_waitcnt vmcnt(7)
	v_mov_b32_e32 v20, v218
	v_mov_b32_e32 v21, v219
	v_lshlrev_b32_e32 v38, 16, v20
	v_and_b32_e32 v39, 0xffff0000, v20
	v_lshlrev_b32_e32 v20, 16, v21
	v_and_b32_e32 v21, 0xffff0000, v21
	v_pk_mul_f32 v[22:23], v[22:23], v[38:39]
	v_pk_mul_f32 v[20:21], v[24:25], v[20:21]
	v_cvt_pk_bf16_f32 v22, v22, v23
	v_cvt_pk_bf16_f32 v23, v20, v21
	global_store_dwordx2 v[18:19], v[22:23], off offset:16
	v_pk_mul_f32 v[24:25], v[26:27], v[34:35] op_sel_hi:[1,0]
	s_waitcnt vmcnt(7)
	v_mov_b32_e32 v20, v220
	v_mov_b32_e32 v21, v221
	v_lshlrev_b32_e32 v22, 16, v20
	v_and_b32_e32 v23, 0xffff0000, v20
	v_lshlrev_b32_e32 v20, 16, v21
	v_and_b32_e32 v21, 0xffff0000, v21
	v_pk_mul_f32 v[22:23], v[24:25], v[22:23]
	v_pk_mul_f32 v[24:25], v[28:29], v[34:35] op_sel_hi:[1,0]
	v_cvt_pk_bf16_f32 v22, v22, v23
	v_pk_mul_f32 v[20:21], v[24:25], v[20:21]
	v_pk_mul_f32 v[24:25], v[30:31], v[34:35] op_sel_hi:[1,0]
	v_cvt_pk_bf16_f32 v23, v20, v21
	global_store_dwordx2 v[18:19], v[22:23], off offset:32
	s_waitcnt vmcnt(7)
	v_mov_b32_e32 v20, v222
	v_mov_b32_e32 v21, v223
	v_lshlrev_b32_e32 v22, 16, v20
	v_and_b32_e32 v23, 0xffff0000, v20
	v_lshlrev_b32_e32 v20, 16, v21
	v_and_b32_e32 v21, 0xffff0000, v21
	v_pk_mul_f32 v[22:23], v[24:25], v[22:23]
	v_pk_mul_f32 v[24:25], v[32:33], v[34:35] op_sel_hi:[1,0]
	v_cvt_pk_bf16_f32 v22, v22, v23
	v_pk_mul_f32 v[20:21], v[24:25], v[20:21]
	s_nop 0
	v_cvt_pk_bf16_f32 v23, v20, v21
	global_store_dwordx2 v[18:19], v[22:23], off offset:48
	s_waitcnt vmcnt(7)
	v_mov_b32_e32 v20, v224
	v_mov_b32_e32 v21, v225
	v_lshlrev_b32_e32 v22, 16, v20
	v_and_b32_e32 v23, 0xffff0000, v20
	v_lshlrev_b32_e32 v20, 16, v21
	v_and_b32_e32 v21, 0xffff0000, v21
	v_pk_mul_f32 v[2:3], v[2:3], v[22:23]
	v_pk_mul_f32 v[4:5], v[4:5], v[20:21]
	v_cvt_pk_bf16_f32 v2, v2, v3
	v_cvt_pk_bf16_f32 v3, v4, v5
	global_store_dwordx2 v[18:19], v[2:3], off offset:64
	s_waitcnt vmcnt(7)
	v_mov_b32_e32 v2, v226
	v_mov_b32_e32 v3, v227
	v_lshlrev_b32_e32 v4, 16, v2
	v_and_b32_e32 v5, 0xffff0000, v2
	v_lshlrev_b32_e32 v2, 16, v3
	v_and_b32_e32 v3, 0xffff0000, v3
	v_pk_mul_f32 v[4:5], v[6:7], v[4:5]
	v_pk_mul_f32 v[6:7], v[8:9], v[34:35] op_sel_hi:[1,0]
	v_cvt_pk_bf16_f32 v4, v4, v5
	v_pk_mul_f32 v[2:3], v[6:7], v[2:3]
	v_pk_mul_f32 v[6:7], v[10:11], v[34:35] op_sel_hi:[1,0]
	v_cvt_pk_bf16_f32 v5, v2, v3
	global_store_dwordx2 v[18:19], v[4:5], off offset:80
	s_waitcnt vmcnt(7)
	v_mov_b32_e32 v2, v228
	v_mov_b32_e32 v3, v229
	v_lshlrev_b32_e32 v4, 16, v2
	v_and_b32_e32 v5, 0xffff0000, v2
	v_lshlrev_b32_e32 v2, 16, v3
	v_and_b32_e32 v3, 0xffff0000, v3
	v_pk_mul_f32 v[4:5], v[6:7], v[4:5]
	v_pk_mul_f32 v[6:7], v[12:13], v[34:35] op_sel_hi:[1,0]
	v_cvt_pk_bf16_f32 v4, v4, v5
	v_pk_mul_f32 v[2:3], v[6:7], v[2:3]
	v_pk_mul_f32 v[6:7], v[14:15], v[34:35] op_sel_hi:[1,0]
	v_cvt_pk_bf16_f32 v5, v2, v3
	global_store_dwordx2 v[18:19], v[4:5], off offset:96
	s_waitcnt vmcnt(7)
	v_mov_b32_e32 v2, v230
	v_mov_b32_e32 v3, v231
	v_lshlrev_b32_e32 v4, 16, v2
	v_and_b32_e32 v5, 0xffff0000, v2
	v_lshlrev_b32_e32 v2, 16, v3
	v_and_b32_e32 v3, 0xffff0000, v3
	v_pk_mul_f32 v[4:5], v[6:7], v[4:5]
	v_pk_mul_f32 v[6:7], v[16:17], v[34:35] op_sel_hi:[1,0]
	v_cvt_pk_bf16_f32 v4, v4, v5
	v_pk_mul_f32 v[2:3], v[6:7], v[2:3]
	s_nop 0
	v_cvt_pk_bf16_f32 v5, v2, v3
	global_store_dwordx2 v[18:19], v[4:5], off offset:112
	s_cbranch_scc1 .LBB0_69
